# rotK tab3 + nt hint on P0's once-read xp row loads
# speedup vs baseline: 1.0250x; 1.0250x over previous
; __device__ __forceinline__ void phase0(const Params& P, LAS unsigned char* lds, int tid, int lane, int wave) {
;     ...
;     for (int m = gw; m < MT; m += NGW) {
;         f32x4 v[4]; float ss = 0.f;
; #pragma unroll
;         for (int j = 0; j < 4; ++j) { v[j] = nv[j]; ss += (v[j][0] * v[j][0] + v[j][1] * v[j][1]) + (v[j][2] * v[j][2] + v[j][3] * v[j][3]); }
;         if (m + NGW < MT) {
;             const int mn = m + NGW;
;             const float* xrow = (mn < MP) ? P.xp + (size_t)mn * 1024 : P.xs + (size_t)(mn - MP) * 1024;
; #pragma unroll
;             for (int j = 0; j < 4; ++j) nv[j] = *(const f32x4*)(xrow + 4 * lane + 256 * j);
;         }
.LBB0_31:
	s_add_i32 s41, s84, s3
	s_add_i32 s18, s41, 0x10000
	s_cmp_gt_i32 s18, 0x100ff
	s_cselect_b64 s[26:27], -1, 0
	s_cmp_lt_i32 s18, 0x10100
	s_waitcnt vmcnt(3)
	v_mov_b32_e32 v146, v174
	v_mov_b32_e32 v147, v175
	v_mov_b32_e32 v148, v176
	v_mov_b32_e32 v149, v177
	s_waitcnt vmcnt(2)
	v_mov_b32_e32 v150, v170
	v_mov_b32_e32 v151, v171
	v_mov_b32_e32 v152, v172
	v_mov_b32_e32 v153, v173
	s_waitcnt vmcnt(1)
	v_mov_b32_e32 v154, v166
	v_mov_b32_e32 v155, v167
	v_mov_b32_e32 v156, v168
	v_mov_b32_e32 v157, v169
	s_waitcnt vmcnt(0)
	v_mov_b32_e32 v158, v162
	v_mov_b32_e32 v159, v163
	v_mov_b32_e32 v160, v164
	v_mov_b32_e32 v161, v165
	s_cbranch_scc0 .LBB0_33
	s_add_u32 s42, s28, s24
	s_addc_u32 s19, s29, s25
	s_cmp_lt_i32 s18, 0x10000
	s_cselect_b32 s19, s19, 0
	s_cselect_b32 s18, s42, s41
	s_cselect_b32 s42, s69, s71
	s_cselect_b32 s43, s68, s70
	s_lshl_b64 s[18:19], s[18:19], 12
	s_add_u32 s18, s43, s18
	s_addc_u32 s19, s42, s19
	global_load_dwordx4 v[146:149], v191, s[18:19] nt
	global_load_dwordx4 v[150:153], v191, s[18:19] offset:1024 nt
	global_load_dwordx4 v[154:157], v191, s[18:19] offset:2048 nt
	global_load_dwordx4 v[158:161], v191, s[18:19] offset:3072 nt
